# v1 + removed per-tile vmcnt(0) drain in gate/up GEMM + SSD inter-chunk scan (S2) rewritten: 32 decay loads hoisted, 8-deep state prefetch, counted waits
# baseline (speedup 1.0000x reference)
; __device__ __forceinline__ int tid_l() { int t = threadIdx.x; asm volatile("" : "+v"(t)); return t; }
; __device__ __forceinline__ unsigned cvt_pk(float lo, float hi) { return pg8::cvt_pk_bf16(lo, hi); }
; __device__ __forceinline__ float bf_lo(unsigned u) { return __uint_as_float(u << 16); }
; __device__ __forceinline__ float bf_hi(unsigned u) { return __uint_as_float(u & 0xffff0000u); }
; __device__ __forceinline__ void s2_phase(const Bufs& B) {
;     const int nthr = gridDim.x * 512;
;     for (int idx = blockIdx.x * 512 + tid_l(); idx < NB * 32 * 64 * 16; idx += nthr) {
;         const int n8 = idx & 15, p = (idx >> 4) & 63, head = (idx >> 10) & 31, b = idx >> 15;
;         float hacc[8];
; #pragma unroll
;         for (int e = 0; e < 8; ++e) hacc[e] = 0.f;
;         const size_t base = (((size_t)b * NCHUNK) * 32 + head) * 8192 + p * 128 + 8 * n8;
;         u32x4 nxt = *(const u32x4*)(B.states + base);
; #pragma unroll 4
;         for (int c = 0; c < NCHUNK; ++c) {
;             const size_t off = base + (size_t)c * 32 * 8192;
;             const u32x4 st = nxt;
;             if (c + 1 < NCHUNK) nxt = *(const u32x4*)(B.states + off + (size_t)32 * 8192);
;             u32x4 o;
; #pragma unroll
;             for (int q = 0; q < 4; ++q) o[q] = cvt_pk(hacc[2 * q], hacc[2 * q + 1]);
;             *(u32x4*)(B.hprev + off) = o;
;             const float dec = __expf(B.alast[(b * NCHUNK + c) * 32 + head]);
; #pragma unroll
;             for (int q = 0; q < 4; ++q) { hacc[2 * q] = hacc[2 * q] * dec + bf_lo(st[q]); hacc[2 * q + 1] = hacc[2 * q + 1] * dec + bf_hi(st[q]); }
;         }
.LBB0_208:
	v_ashrrev_i32_e32 v2, 15, v0
	v_and_b32_e32 v3, 0x7fff, v0
	v_lshlrev_b32_e32 v3, 4, v3
	v_lshl_or_b32 v4, v2, 24, v3
	v_mov_b32_e32 v5, 0
	s_add_u32 s10, s76, 0x9700000
	s_addc_u32 s11, s77, 0
	v_lshl_add_u64 v[6:7], s[4:5], 0, v[4:5]
	v_lshl_add_u64 v[8:9], s[10:11], 0, v[4:5]
	v_bfe_u32 v10, v0, 10, 5
	v_lshl_or_b32 v10, v2, 10, v10
	v_mov_b32_e32 v11, 0
	s_mov_b32 s10, 0x80000
	s_mov_b32 s11, 0
	v_lshl_add_u64 v[10:11], v[10:11], 2, v[166:167]
	v_lshl_add_u64 v[10:11], s[76:77], 0, v[10:11]
	global_load_dword v48, v[10:11], off
	global_load_dword v49, v[10:11], off offset:128
	global_load_dword v50, v[10:11], off offset:256
	global_load_dword v51, v[10:11], off offset:384
	global_load_dword v52, v[10:11], off offset:512
	global_load_dword v53, v[10:11], off offset:640
	global_load_dword v54, v[10:11], off offset:768
	global_load_dword v55, v[10:11], off offset:896
	global_load_dword v56, v[10:11], off offset:1024
	global_load_dword v57, v[10:11], off offset:1152
	global_load_dword v58, v[10:11], off offset:1280
	global_load_dword v59, v[10:11], off offset:1408
	global_load_dword v60, v[10:11], off offset:1536
	global_load_dword v61, v[10:11], off offset:1664
	global_load_dword v62, v[10:11], off offset:1792
	global_load_dword v63, v[10:11], off offset:1920
	global_load_dword v64, v[10:11], off offset:2048
	global_load_dword v65, v[10:11], off offset:2176
	global_load_dword v66, v[10:11], off offset:2304
	global_load_dword v67, v[10:11], off offset:2432
	global_load_dword v68, v[10:11], off offset:2560
	global_load_dword v69, v[10:11], off offset:2688
	global_load_dword v70, v[10:11], off offset:2816
	global_load_dword v71, v[10:11], off offset:2944
	global_load_dword v72, v[10:11], off offset:3072
	global_load_dword v73, v[10:11], off offset:3200
	global_load_dword v74, v[10:11], off offset:3328
	global_load_dword v75, v[10:11], off offset:3456
	global_load_dword v76, v[10:11], off offset:3584
	global_load_dword v77, v[10:11], off offset:3712
	global_load_dword v78, v[10:11], off offset:3840
	global_load_dword v79, v[10:11], off offset:3968
	global_load_dwordx4 v[16:19], v[6:7], off
	v_lshl_add_u64 v[6:7], v[6:7], 0, s[10:11]
	global_load_dwordx4 v[20:23], v[6:7], off
	v_lshl_add_u64 v[6:7], v[6:7], 0, s[10:11]
	global_load_dwordx4 v[24:27], v[6:7], off
	v_lshl_add_u64 v[6:7], v[6:7], 0, s[10:11]
	global_load_dwordx4 v[28:31], v[6:7], off
	v_lshl_add_u64 v[6:7], v[6:7], 0, s[10:11]
	global_load_dwordx4 v[32:35], v[6:7], off
	v_lshl_add_u64 v[6:7], v[6:7], 0, s[10:11]
	global_load_dwordx4 v[36:39], v[6:7], off
	v_lshl_add_u64 v[6:7], v[6:7], 0, s[10:11]
	global_load_dwordx4 v[40:43], v[6:7], off
	v_lshl_add_u64 v[6:7], v[6:7], 0, s[10:11]
	global_load_dwordx4 v[44:47], v[6:7], off
	v_lshl_add_u64 v[6:7], v[6:7], 0, s[10:11]
	v_mov_b32_e32 v80, 0
	v_mov_b32_e32 v81, 0
	v_mov_b32_e32 v82, 0
	v_mov_b32_e32 v83, 0
	v_mov_b32_e32 v84, 0
	v_mov_b32_e32 v85, 0
	v_mov_b32_e32 v86, 0
	v_mov_b32_e32 v87, 0
	s_waitcnt vmcnt(8)
	v_mul_f32_e32 v48, 0x3fb8aa3b, v48
	v_mul_f32_e32 v49, 0x3fb8aa3b, v49
	v_mul_f32_e32 v50, 0x3fb8aa3b, v50
	v_mul_f32_e32 v51, 0x3fb8aa3b, v51
	v_mul_f32_e32 v52, 0x3fb8aa3b, v52
	v_mul_f32_e32 v53, 0x3fb8aa3b, v53
	v_mul_f32_e32 v54, 0x3fb8aa3b, v54
	v_mul_f32_e32 v55, 0x3fb8aa3b, v55
	v_mul_f32_e32 v56, 0x3fb8aa3b, v56
	v_mul_f32_e32 v57, 0x3fb8aa3b, v57
	v_mul_f32_e32 v58, 0x3fb8aa3b, v58
	v_mul_f32_e32 v59, 0x3fb8aa3b, v59
	v_mul_f32_e32 v60, 0x3fb8aa3b, v60
	v_mul_f32_e32 v61, 0x3fb8aa3b, v61
	v_mul_f32_e32 v62, 0x3fb8aa3b, v62
	v_mul_f32_e32 v63, 0x3fb8aa3b, v63
	v_mul_f32_e32 v64, 0x3fb8aa3b, v64
	v_mul_f32_e32 v65, 0x3fb8aa3b, v65
	v_mul_f32_e32 v66, 0x3fb8aa3b, v66
	v_mul_f32_e32 v67, 0x3fb8aa3b, v67
	v_mul_f32_e32 v68, 0x3fb8aa3b, v68
	v_mul_f32_e32 v69, 0x3fb8aa3b, v69
	v_mul_f32_e32 v70, 0x3fb8aa3b, v70
	v_mul_f32_e32 v71, 0x3fb8aa3b, v71
	v_mul_f32_e32 v72, 0x3fb8aa3b, v72
	v_mul_f32_e32 v73, 0x3fb8aa3b, v73
	v_mul_f32_e32 v74, 0x3fb8aa3b, v74
	v_mul_f32_e32 v75, 0x3fb8aa3b, v75
	v_mul_f32_e32 v76, 0x3fb8aa3b, v76
	v_mul_f32_e32 v77, 0x3fb8aa3b, v77
	v_mul_f32_e32 v78, 0x3fb8aa3b, v78
	v_mul_f32_e32 v79, 0x3fb8aa3b, v79
	v_exp_f32_e32 v48, v48
	v_exp_f32_e32 v49, v49
	v_exp_f32_e32 v50, v50
	v_exp_f32_e32 v51, v51
	v_exp_f32_e32 v52, v52
	v_exp_f32_e32 v53, v53
	v_exp_f32_e32 v54, v54
	v_exp_f32_e32 v55, v55
	v_exp_f32_e32 v56, v56
	v_exp_f32_e32 v57, v57
	v_exp_f32_e32 v58, v58
	v_exp_f32_e32 v59, v59
	v_exp_f32_e32 v60, v60
	v_exp_f32_e32 v61, v61
	v_exp_f32_e32 v62, v62
	v_exp_f32_e32 v63, v63
	v_exp_f32_e32 v64, v64
	v_exp_f32_e32 v65, v65
	v_exp_f32_e32 v66, v66
	v_exp_f32_e32 v67, v67
	v_exp_f32_e32 v68, v68
	v_exp_f32_e32 v69, v69
	v_exp_f32_e32 v70, v70
	v_exp_f32_e32 v71, v71
	v_exp_f32_e32 v72, v72
	v_exp_f32_e32 v73, v73
	v_exp_f32_e32 v74, v74
	v_exp_f32_e32 v75, v75
	v_exp_f32_e32 v76, v76
	v_exp_f32_e32 v77, v77
	v_exp_f32_e32 v78, v78
	v_exp_f32_e32 v79, v79
	v_cvt_pk_bf16_f32 v12, v80, v81
	v_cvt_pk_bf16_f32 v13, v82, v83
	v_cvt_pk_bf16_f32 v14, v84, v85
	v_cvt_pk_bf16_f32 v15, v86, v87
	global_store_dwordx4 v[8:9], v[12:15], off
	v_lshl_add_u64 v[8:9], v[8:9], 0, s[10:11]
	s_waitcnt vmcnt(8)
	v_lshlrev_b32_e32 v88, 16, v16
	v_and_b32_e32 v89, 0xffff0000, v16
	v_lshlrev_b32_e32 v90, 16, v17
	v_and_b32_e32 v91, 0xffff0000, v17
	v_lshlrev_b32_e32 v92, 16, v18
	v_and_b32_e32 v93, 0xffff0000, v18
	v_lshlrev_b32_e32 v94, 16, v19
	v_and_b32_e32 v95, 0xffff0000, v19
	global_load_dwordx4 v[16:19], v[6:7], off
	v_lshl_add_u64 v[6:7], v[6:7], 0, s[10:11]
	v_pk_fma_f32 v[80:81], v[80:81], v[48:49], v[88:89] op_sel_hi:[1,0,1]
	v_pk_fma_f32 v[82:83], v[82:83], v[48:49], v[90:91] op_sel_hi:[1,0,1]
	v_pk_fma_f32 v[84:85], v[84:85], v[48:49], v[92:93] op_sel_hi:[1,0,1]
	v_pk_fma_f32 v[86:87], v[86:87], v[48:49], v[94:95] op_sel_hi:[1,0,1]
	v_cvt_pk_bf16_f32 v12, v80, v81
	v_cvt_pk_bf16_f32 v13, v82, v83
	v_cvt_pk_bf16_f32 v14, v84, v85
	v_cvt_pk_bf16_f32 v15, v86, v87
	global_store_dwordx4 v[8:9], v[12:15], off
	v_lshl_add_u64 v[8:9], v[8:9], 0, s[10:11]
	s_waitcnt vmcnt(9)
; __device__ __forceinline__ unsigned cvt_pk(float lo, float hi) { return pg8::cvt_pk_bf16(lo, hi); }
; __device__ __forceinline__ float bf_lo(unsigned u) { return __uint_as_float(u << 16); }
; __device__ __forceinline__ float bf_hi(unsigned u) { return __uint_as_float(u & 0xffff0000u); }
; __device__ __forceinline__ void s2_phase(const Bufs& B) {
;     ...
;         u32x4 nxt = *(const u32x4*)(B.states + base);
; #pragma unroll 4
;         for (int c = 0; c < NCHUNK; ++c) {
;             const size_t off = base + (size_t)c * 32 * 8192;
;             const u32x4 st = nxt;
;             if (c + 1 < NCHUNK) nxt = *(const u32x4*)(B.states + off + (size_t)32 * 8192);
;             u32x4 o;
; #pragma unroll
;             for (int q = 0; q < 4; ++q) o[q] = cvt_pk(hacc[2 * q], hacc[2 * q + 1]);
;             *(u32x4*)(B.hprev + off) = o;
;             const float dec = __expf(B.alast[(b * NCHUNK + c) * 32 + head]);
; #pragma unroll
;             for (int q = 0; q < 4; ++q) { hacc[2 * q] = hacc[2 * q] * dec + bf_lo(st[q]); hacc[2 * q + 1] = hacc[2 * q + 1] * dec + bf_hi(st[q]); }
;         }
	v_lshlrev_b32_e32 v88, 16, v20
	v_and_b32_e32 v89, 0xffff0000, v20
	v_lshlrev_b32_e32 v90, 16, v21
	v_and_b32_e32 v91, 0xffff0000, v21
	v_lshlrev_b32_e32 v92, 16, v22
	v_and_b32_e32 v93, 0xffff0000, v22
	v_lshlrev_b32_e32 v94, 16, v23
	v_and_b32_e32 v95, 0xffff0000, v23
	global_load_dwordx4 v[20:23], v[6:7], off
	v_lshl_add_u64 v[6:7], v[6:7], 0, s[10:11]
	v_pk_fma_f32 v[80:81], v[80:81], v[48:49], v[88:89] op_sel:[0,1,0] op_sel_hi:[1,1,1]
	v_pk_fma_f32 v[82:83], v[82:83], v[48:49], v[90:91] op_sel:[0,1,0] op_sel_hi:[1,1,1]
	v_pk_fma_f32 v[84:85], v[84:85], v[48:49], v[92:93] op_sel:[0,1,0] op_sel_hi:[1,1,1]
	v_pk_fma_f32 v[86:87], v[86:87], v[48:49], v[94:95] op_sel:[0,1,0] op_sel_hi:[1,1,1]
	v_cvt_pk_bf16_f32 v12, v80, v81
	v_cvt_pk_bf16_f32 v13, v82, v83
	v_cvt_pk_bf16_f32 v14, v84, v85
	v_cvt_pk_bf16_f32 v15, v86, v87
	global_store_dwordx4 v[8:9], v[12:15], off
	v_lshl_add_u64 v[8:9], v[8:9], 0, s[10:11]
	s_waitcnt vmcnt(10)
	v_lshlrev_b32_e32 v88, 16, v24
	v_and_b32_e32 v89, 0xffff0000, v24
	v_lshlrev_b32_e32 v90, 16, v25
	v_and_b32_e32 v91, 0xffff0000, v25
	v_lshlrev_b32_e32 v92, 16, v26
	v_and_b32_e32 v93, 0xffff0000, v26
	v_lshlrev_b32_e32 v94, 16, v27
	v_and_b32_e32 v95, 0xffff0000, v27
	global_load_dwordx4 v[24:27], v[6:7], off
	v_lshl_add_u64 v[6:7], v[6:7], 0, s[10:11]
	v_pk_fma_f32 v[80:81], v[80:81], v[50:51], v[88:89] op_sel_hi:[1,0,1]
	v_pk_fma_f32 v[82:83], v[82:83], v[50:51], v[90:91] op_sel_hi:[1,0,1]
	v_pk_fma_f32 v[84:85], v[84:85], v[50:51], v[92:93] op_sel_hi:[1,0,1]
	v_pk_fma_f32 v[86:87], v[86:87], v[50:51], v[94:95] op_sel_hi:[1,0,1]
	v_cvt_pk_bf16_f32 v12, v80, v81
	v_cvt_pk_bf16_f32 v13, v82, v83
	v_cvt_pk_bf16_f32 v14, v84, v85
	v_cvt_pk_bf16_f32 v15, v86, v87
	global_store_dwordx4 v[8:9], v[12:15], off
	v_lshl_add_u64 v[8:9], v[8:9], 0, s[10:11]
	s_waitcnt vmcnt(11)
	v_lshlrev_b32_e32 v88, 16, v28
	v_and_b32_e32 v89, 0xffff0000, v28
	v_lshlrev_b32_e32 v90, 16, v29
	v_and_b32_e32 v91, 0xffff0000, v29
	v_lshlrev_b32_e32 v92, 16, v30
	v_and_b32_e32 v93, 0xffff0000, v30
	v_lshlrev_b32_e32 v94, 16, v31
	v_and_b32_e32 v95, 0xffff0000, v31
	global_load_dwordx4 v[28:31], v[6:7], off
	v_lshl_add_u64 v[6:7], v[6:7], 0, s[10:11]
	v_pk_fma_f32 v[80:81], v[80:81], v[50:51], v[88:89] op_sel:[0,1,0] op_sel_hi:[1,1,1]
	v_pk_fma_f32 v[82:83], v[82:83], v[50:51], v[90:91] op_sel:[0,1,0] op_sel_hi:[1,1,1]
	v_pk_fma_f32 v[84:85], v[84:85], v[50:51], v[92:93] op_sel:[0,1,0] op_sel_hi:[1,1,1]
	v_pk_fma_f32 v[86:87], v[86:87], v[50:51], v[94:95] op_sel:[0,1,0] op_sel_hi:[1,1,1]
	v_cvt_pk_bf16_f32 v12, v80, v81
	v_cvt_pk_bf16_f32 v13, v82, v83
	v_cvt_pk_bf16_f32 v14, v84, v85
	v_cvt_pk_bf16_f32 v15, v86, v87
	global_store_dwordx4 v[8:9], v[12:15], off
	v_lshl_add_u64 v[8:9], v[8:9], 0, s[10:11]
	s_waitcnt vmcnt(12)
	v_lshlrev_b32_e32 v88, 16, v32
	v_and_b32_e32 v89, 0xffff0000, v32
	v_lshlrev_b32_e32 v90, 16, v33
	v_and_b32_e32 v91, 0xffff0000, v33
	v_lshlrev_b32_e32 v92, 16, v34
	v_and_b32_e32 v93, 0xffff0000, v34
	v_lshlrev_b32_e32 v94, 16, v35
	v_and_b32_e32 v95, 0xffff0000, v35
	global_load_dwordx4 v[32:35], v[6:7], off
	v_lshl_add_u64 v[6:7], v[6:7], 0, s[10:11]
	v_pk_fma_f32 v[80:81], v[80:81], v[52:53], v[88:89] op_sel_hi:[1,0,1]
	v_pk_fma_f32 v[82:83], v[82:83], v[52:53], v[90:91] op_sel_hi:[1,0,1]
	v_pk_fma_f32 v[84:85], v[84:85], v[52:53], v[92:93] op_sel_hi:[1,0,1]
	v_pk_fma_f32 v[86:87], v[86:87], v[52:53], v[94:95] op_sel_hi:[1,0,1]
	v_cvt_pk_bf16_f32 v12, v80, v81
	v_cvt_pk_bf16_f32 v13, v82, v83
	v_cvt_pk_bf16_f32 v14, v84, v85
	v_cvt_pk_bf16_f32 v15, v86, v87
	global_store_dwordx4 v[8:9], v[12:15], off
	v_lshl_add_u64 v[8:9], v[8:9], 0, s[10:11]
	s_waitcnt vmcnt(13)
	v_lshlrev_b32_e32 v88, 16, v36
	v_and_b32_e32 v89, 0xffff0000, v36
	v_lshlrev_b32_e32 v90, 16, v37
	v_and_b32_e32 v91, 0xffff0000, v37
	v_lshlrev_b32_e32 v92, 16, v38
	v_and_b32_e32 v93, 0xffff0000, v38
	v_lshlrev_b32_e32 v94, 16, v39
	v_and_b32_e32 v95, 0xffff0000, v39
	global_load_dwordx4 v[36:39], v[6:7], off
	v_lshl_add_u64 v[6:7], v[6:7], 0, s[10:11]
	v_pk_fma_f32 v[80:81], v[80:81], v[52:53], v[88:89] op_sel:[0,1,0] op_sel_hi:[1,1,1]
	v_pk_fma_f32 v[82:83], v[82:83], v[52:53], v[90:91] op_sel:[0,1,0] op_sel_hi:[1,1,1]
	v_pk_fma_f32 v[84:85], v[84:85], v[52:53], v[92:93] op_sel:[0,1,0] op_sel_hi:[1,1,1]
	v_pk_fma_f32 v[86:87], v[86:87], v[52:53], v[94:95] op_sel:[0,1,0] op_sel_hi:[1,1,1]
	v_cvt_pk_bf16_f32 v12, v80, v81
	v_cvt_pk_bf16_f32 v13, v82, v83
	v_cvt_pk_bf16_f32 v14, v84, v85
	v_cvt_pk_bf16_f32 v15, v86, v87
	global_store_dwordx4 v[8:9], v[12:15], off
	v_lshl_add_u64 v[8:9], v[8:9], 0, s[10:11]
	s_waitcnt vmcnt(14)
	v_lshlrev_b32_e32 v88, 16, v40
	v_and_b32_e32 v89, 0xffff0000, v40
	v_lshlrev_b32_e32 v90, 16, v41
	v_and_b32_e32 v91, 0xffff0000, v41
	v_lshlrev_b32_e32 v92, 16, v42
	v_and_b32_e32 v93, 0xffff0000, v42
	v_lshlrev_b32_e32 v94, 16, v43
	v_and_b32_e32 v95, 0xffff0000, v43
	global_load_dwordx4 v[40:43], v[6:7], off
	v_lshl_add_u64 v[6:7], v[6:7], 0, s[10:11]
	v_pk_fma_f32 v[80:81], v[80:81], v[54:55], v[88:89] op_sel_hi:[1,0,1]
	v_pk_fma_f32 v[82:83], v[82:83], v[54:55], v[90:91] op_sel_hi:[1,0,1]
	v_pk_fma_f32 v[84:85], v[84:85], v[54:55], v[92:93] op_sel_hi:[1,0,1]
	v_pk_fma_f32 v[86:87], v[86:87], v[54:55], v[94:95] op_sel_hi:[1,0,1]
	v_cvt_pk_bf16_f32 v12, v80, v81
	v_cvt_pk_bf16_f32 v13, v82, v83
	v_cvt_pk_bf16_f32 v14, v84, v85
	v_cvt_pk_bf16_f32 v15, v86, v87
	global_store_dwordx4 v[8:9], v[12:15], off
	v_lshl_add_u64 v[8:9], v[8:9], 0, s[10:11]
	s_waitcnt vmcnt(15)
; __device__ __forceinline__ unsigned cvt_pk(float lo, float hi) { return pg8::cvt_pk_bf16(lo, hi); }
; __device__ __forceinline__ float bf_lo(unsigned u) { return __uint_as_float(u << 16); }
; __device__ __forceinline__ float bf_hi(unsigned u) { return __uint_as_float(u & 0xffff0000u); }
; __device__ __forceinline__ void s2_phase(const Bufs& B) {
;     ...
;         u32x4 nxt = *(const u32x4*)(B.states + base);
; #pragma unroll 4
;         for (int c = 0; c < NCHUNK; ++c) {
;             const size_t off = base + (size_t)c * 32 * 8192;
;             const u32x4 st = nxt;
;             if (c + 1 < NCHUNK) nxt = *(const u32x4*)(B.states + off + (size_t)32 * 8192);
;             u32x4 o;
; #pragma unroll
;             for (int q = 0; q < 4; ++q) o[q] = cvt_pk(hacc[2 * q], hacc[2 * q + 1]);
;             *(u32x4*)(B.hprev + off) = o;
;             const float dec = __expf(B.alast[(b * NCHUNK + c) * 32 + head]);
; #pragma unroll
;             for (int q = 0; q < 4; ++q) { hacc[2 * q] = hacc[2 * q] * dec + bf_lo(st[q]); hacc[2 * q + 1] = hacc[2 * q + 1] * dec + bf_hi(st[q]); }
;         }
	v_lshlrev_b32_e32 v88, 16, v44
	v_and_b32_e32 v89, 0xffff0000, v44
	v_lshlrev_b32_e32 v90, 16, v45
	v_and_b32_e32 v91, 0xffff0000, v45
	v_lshlrev_b32_e32 v92, 16, v46
	v_and_b32_e32 v93, 0xffff0000, v46
	v_lshlrev_b32_e32 v94, 16, v47
	v_and_b32_e32 v95, 0xffff0000, v47
	global_load_dwordx4 v[44:47], v[6:7], off
	v_lshl_add_u64 v[6:7], v[6:7], 0, s[10:11]
	v_pk_fma_f32 v[80:81], v[80:81], v[54:55], v[88:89] op_sel:[0,1,0] op_sel_hi:[1,1,1]
	v_pk_fma_f32 v[82:83], v[82:83], v[54:55], v[90:91] op_sel:[0,1,0] op_sel_hi:[1,1,1]
	v_pk_fma_f32 v[84:85], v[84:85], v[54:55], v[92:93] op_sel:[0,1,0] op_sel_hi:[1,1,1]
	v_pk_fma_f32 v[86:87], v[86:87], v[54:55], v[94:95] op_sel:[0,1,0] op_sel_hi:[1,1,1]
	v_cvt_pk_bf16_f32 v12, v80, v81
	v_cvt_pk_bf16_f32 v13, v82, v83
	v_cvt_pk_bf16_f32 v14, v84, v85
	v_cvt_pk_bf16_f32 v15, v86, v87
	global_store_dwordx4 v[8:9], v[12:15], off
	v_lshl_add_u64 v[8:9], v[8:9], 0, s[10:11]
	s_waitcnt vmcnt(15)
	v_lshlrev_b32_e32 v88, 16, v16
	v_and_b32_e32 v89, 0xffff0000, v16
	v_lshlrev_b32_e32 v90, 16, v17
	v_and_b32_e32 v91, 0xffff0000, v17
	v_lshlrev_b32_e32 v92, 16, v18
	v_and_b32_e32 v93, 0xffff0000, v18
	v_lshlrev_b32_e32 v94, 16, v19
	v_and_b32_e32 v95, 0xffff0000, v19
	global_load_dwordx4 v[16:19], v[6:7], off
	v_lshl_add_u64 v[6:7], v[6:7], 0, s[10:11]
	v_pk_fma_f32 v[80:81], v[80:81], v[56:57], v[88:89] op_sel_hi:[1,0,1]
	v_pk_fma_f32 v[82:83], v[82:83], v[56:57], v[90:91] op_sel_hi:[1,0,1]
	v_pk_fma_f32 v[84:85], v[84:85], v[56:57], v[92:93] op_sel_hi:[1,0,1]
	v_pk_fma_f32 v[86:87], v[86:87], v[56:57], v[94:95] op_sel_hi:[1,0,1]
	v_cvt_pk_bf16_f32 v12, v80, v81
	v_cvt_pk_bf16_f32 v13, v82, v83
	v_cvt_pk_bf16_f32 v14, v84, v85
	v_cvt_pk_bf16_f32 v15, v86, v87
	global_store_dwordx4 v[8:9], v[12:15], off
	v_lshl_add_u64 v[8:9], v[8:9], 0, s[10:11]
	s_waitcnt vmcnt(15)
	v_lshlrev_b32_e32 v88, 16, v20
	v_and_b32_e32 v89, 0xffff0000, v20
	v_lshlrev_b32_e32 v90, 16, v21
	v_and_b32_e32 v91, 0xffff0000, v21
	v_lshlrev_b32_e32 v92, 16, v22
	v_and_b32_e32 v93, 0xffff0000, v22
	v_lshlrev_b32_e32 v94, 16, v23
	v_and_b32_e32 v95, 0xffff0000, v23
	global_load_dwordx4 v[20:23], v[6:7], off
	v_lshl_add_u64 v[6:7], v[6:7], 0, s[10:11]
	v_pk_fma_f32 v[80:81], v[80:81], v[56:57], v[88:89] op_sel:[0,1,0] op_sel_hi:[1,1,1]
	v_pk_fma_f32 v[82:83], v[82:83], v[56:57], v[90:91] op_sel:[0,1,0] op_sel_hi:[1,1,1]
	v_pk_fma_f32 v[84:85], v[84:85], v[56:57], v[92:93] op_sel:[0,1,0] op_sel_hi:[1,1,1]
	v_pk_fma_f32 v[86:87], v[86:87], v[56:57], v[94:95] op_sel:[0,1,0] op_sel_hi:[1,1,1]
	v_cvt_pk_bf16_f32 v12, v80, v81
	v_cvt_pk_bf16_f32 v13, v82, v83
	v_cvt_pk_bf16_f32 v14, v84, v85
	v_cvt_pk_bf16_f32 v15, v86, v87
	global_store_dwordx4 v[8:9], v[12:15], off
	v_lshl_add_u64 v[8:9], v[8:9], 0, s[10:11]
	s_waitcnt vmcnt(15)
	v_lshlrev_b32_e32 v88, 16, v24
	v_and_b32_e32 v89, 0xffff0000, v24
	v_lshlrev_b32_e32 v90, 16, v25
	v_and_b32_e32 v91, 0xffff0000, v25
	v_lshlrev_b32_e32 v92, 16, v26
	v_and_b32_e32 v93, 0xffff0000, v26
	v_lshlrev_b32_e32 v94, 16, v27
	v_and_b32_e32 v95, 0xffff0000, v27
	global_load_dwordx4 v[24:27], v[6:7], off
	v_lshl_add_u64 v[6:7], v[6:7], 0, s[10:11]
	v_pk_fma_f32 v[80:81], v[80:81], v[58:59], v[88:89] op_sel_hi:[1,0,1]
	v_pk_fma_f32 v[82:83], v[82:83], v[58:59], v[90:91] op_sel_hi:[1,0,1]
	v_pk_fma_f32 v[84:85], v[84:85], v[58:59], v[92:93] op_sel_hi:[1,0,1]
	v_pk_fma_f32 v[86:87], v[86:87], v[58:59], v[94:95] op_sel_hi:[1,0,1]
	v_cvt_pk_bf16_f32 v12, v80, v81
	v_cvt_pk_bf16_f32 v13, v82, v83
	v_cvt_pk_bf16_f32 v14, v84, v85
	v_cvt_pk_bf16_f32 v15, v86, v87
	global_store_dwordx4 v[8:9], v[12:15], off
	v_lshl_add_u64 v[8:9], v[8:9], 0, s[10:11]
	s_waitcnt vmcnt(15)
	v_lshlrev_b32_e32 v88, 16, v28
	v_and_b32_e32 v89, 0xffff0000, v28
	v_lshlrev_b32_e32 v90, 16, v29
	v_and_b32_e32 v91, 0xffff0000, v29
	v_lshlrev_b32_e32 v92, 16, v30
	v_and_b32_e32 v93, 0xffff0000, v30
	v_lshlrev_b32_e32 v94, 16, v31
	v_and_b32_e32 v95, 0xffff0000, v31
	global_load_dwordx4 v[28:31], v[6:7], off
	v_lshl_add_u64 v[6:7], v[6:7], 0, s[10:11]
	v_pk_fma_f32 v[80:81], v[80:81], v[58:59], v[88:89] op_sel:[0,1,0] op_sel_hi:[1,1,1]
	v_pk_fma_f32 v[82:83], v[82:83], v[58:59], v[90:91] op_sel:[0,1,0] op_sel_hi:[1,1,1]
	v_pk_fma_f32 v[84:85], v[84:85], v[58:59], v[92:93] op_sel:[0,1,0] op_sel_hi:[1,1,1]
	v_pk_fma_f32 v[86:87], v[86:87], v[58:59], v[94:95] op_sel:[0,1,0] op_sel_hi:[1,1,1]
	v_cvt_pk_bf16_f32 v12, v80, v81
	v_cvt_pk_bf16_f32 v13, v82, v83
	v_cvt_pk_bf16_f32 v14, v84, v85
	v_cvt_pk_bf16_f32 v15, v86, v87
	global_store_dwordx4 v[8:9], v[12:15], off
	v_lshl_add_u64 v[8:9], v[8:9], 0, s[10:11]
	s_waitcnt vmcnt(15)
	v_lshlrev_b32_e32 v88, 16, v32
	v_and_b32_e32 v89, 0xffff0000, v32
	v_lshlrev_b32_e32 v90, 16, v33
	v_and_b32_e32 v91, 0xffff0000, v33
	v_lshlrev_b32_e32 v92, 16, v34
	v_and_b32_e32 v93, 0xffff0000, v34
	v_lshlrev_b32_e32 v94, 16, v35
	v_and_b32_e32 v95, 0xffff0000, v35
	global_load_dwordx4 v[32:35], v[6:7], off
	v_lshl_add_u64 v[6:7], v[6:7], 0, s[10:11]
	v_pk_fma_f32 v[80:81], v[80:81], v[60:61], v[88:89] op_sel_hi:[1,0,1]
	v_pk_fma_f32 v[82:83], v[82:83], v[60:61], v[90:91] op_sel_hi:[1,0,1]
	v_pk_fma_f32 v[84:85], v[84:85], v[60:61], v[92:93] op_sel_hi:[1,0,1]
	v_pk_fma_f32 v[86:87], v[86:87], v[60:61], v[94:95] op_sel_hi:[1,0,1]
	v_cvt_pk_bf16_f32 v12, v80, v81
	v_cvt_pk_bf16_f32 v13, v82, v83
	v_cvt_pk_bf16_f32 v14, v84, v85
	v_cvt_pk_bf16_f32 v15, v86, v87
	global_store_dwordx4 v[8:9], v[12:15], off
	v_lshl_add_u64 v[8:9], v[8:9], 0, s[10:11]
	s_waitcnt vmcnt(15)
; __device__ __forceinline__ unsigned cvt_pk(float lo, float hi) { return pg8::cvt_pk_bf16(lo, hi); }
; __device__ __forceinline__ float bf_lo(unsigned u) { return __uint_as_float(u << 16); }
; __device__ __forceinline__ float bf_hi(unsigned u) { return __uint_as_float(u & 0xffff0000u); }
; __device__ __forceinline__ void s2_phase(const Bufs& B) {
;     ...
;         u32x4 nxt = *(const u32x4*)(B.states + base);
; #pragma unroll 4
;         for (int c = 0; c < NCHUNK; ++c) {
;             const size_t off = base + (size_t)c * 32 * 8192;
;             const u32x4 st = nxt;
;             if (c + 1 < NCHUNK) nxt = *(const u32x4*)(B.states + off + (size_t)32 * 8192);
;             u32x4 o;
; #pragma unroll
;             for (int q = 0; q < 4; ++q) o[q] = cvt_pk(hacc[2 * q], hacc[2 * q + 1]);
;             *(u32x4*)(B.hprev + off) = o;
;             const float dec = __expf(B.alast[(b * NCHUNK + c) * 32 + head]);
; #pragma unroll
;             for (int q = 0; q < 4; ++q) { hacc[2 * q] = hacc[2 * q] * dec + bf_lo(st[q]); hacc[2 * q + 1] = hacc[2 * q + 1] * dec + bf_hi(st[q]); }
;         }
	v_lshlrev_b32_e32 v88, 16, v36
	v_and_b32_e32 v89, 0xffff0000, v36
	v_lshlrev_b32_e32 v90, 16, v37
	v_and_b32_e32 v91, 0xffff0000, v37
	v_lshlrev_b32_e32 v92, 16, v38
	v_and_b32_e32 v93, 0xffff0000, v38
	v_lshlrev_b32_e32 v94, 16, v39
	v_and_b32_e32 v95, 0xffff0000, v39
	global_load_dwordx4 v[36:39], v[6:7], off
	v_lshl_add_u64 v[6:7], v[6:7], 0, s[10:11]
	v_pk_fma_f32 v[80:81], v[80:81], v[60:61], v[88:89] op_sel:[0,1,0] op_sel_hi:[1,1,1]
	v_pk_fma_f32 v[82:83], v[82:83], v[60:61], v[90:91] op_sel:[0,1,0] op_sel_hi:[1,1,1]
	v_pk_fma_f32 v[84:85], v[84:85], v[60:61], v[92:93] op_sel:[0,1,0] op_sel_hi:[1,1,1]
	v_pk_fma_f32 v[86:87], v[86:87], v[60:61], v[94:95] op_sel:[0,1,0] op_sel_hi:[1,1,1]
	v_cvt_pk_bf16_f32 v12, v80, v81
	v_cvt_pk_bf16_f32 v13, v82, v83
	v_cvt_pk_bf16_f32 v14, v84, v85
	v_cvt_pk_bf16_f32 v15, v86, v87
	global_store_dwordx4 v[8:9], v[12:15], off
	v_lshl_add_u64 v[8:9], v[8:9], 0, s[10:11]
	s_waitcnt vmcnt(15)
	v_lshlrev_b32_e32 v88, 16, v40
	v_and_b32_e32 v89, 0xffff0000, v40
	v_lshlrev_b32_e32 v90, 16, v41
	v_and_b32_e32 v91, 0xffff0000, v41
	v_lshlrev_b32_e32 v92, 16, v42
	v_and_b32_e32 v93, 0xffff0000, v42
	v_lshlrev_b32_e32 v94, 16, v43
	v_and_b32_e32 v95, 0xffff0000, v43
	global_load_dwordx4 v[40:43], v[6:7], off
	v_lshl_add_u64 v[6:7], v[6:7], 0, s[10:11]
	v_pk_fma_f32 v[80:81], v[80:81], v[62:63], v[88:89] op_sel_hi:[1,0,1]
	v_pk_fma_f32 v[82:83], v[82:83], v[62:63], v[90:91] op_sel_hi:[1,0,1]
	v_pk_fma_f32 v[84:85], v[84:85], v[62:63], v[92:93] op_sel_hi:[1,0,1]
	v_pk_fma_f32 v[86:87], v[86:87], v[62:63], v[94:95] op_sel_hi:[1,0,1]
	v_cvt_pk_bf16_f32 v12, v80, v81
	v_cvt_pk_bf16_f32 v13, v82, v83
	v_cvt_pk_bf16_f32 v14, v84, v85
	v_cvt_pk_bf16_f32 v15, v86, v87
	global_store_dwordx4 v[8:9], v[12:15], off
	v_lshl_add_u64 v[8:9], v[8:9], 0, s[10:11]
	s_waitcnt vmcnt(15)
	v_lshlrev_b32_e32 v88, 16, v44
	v_and_b32_e32 v89, 0xffff0000, v44
	v_lshlrev_b32_e32 v90, 16, v45
	v_and_b32_e32 v91, 0xffff0000, v45
	v_lshlrev_b32_e32 v92, 16, v46
	v_and_b32_e32 v93, 0xffff0000, v46
	v_lshlrev_b32_e32 v94, 16, v47
	v_and_b32_e32 v95, 0xffff0000, v47
	global_load_dwordx4 v[44:47], v[6:7], off
	v_lshl_add_u64 v[6:7], v[6:7], 0, s[10:11]
	v_pk_fma_f32 v[80:81], v[80:81], v[62:63], v[88:89] op_sel:[0,1,0] op_sel_hi:[1,1,1]
	v_pk_fma_f32 v[82:83], v[82:83], v[62:63], v[90:91] op_sel:[0,1,0] op_sel_hi:[1,1,1]
	v_pk_fma_f32 v[84:85], v[84:85], v[62:63], v[92:93] op_sel:[0,1,0] op_sel_hi:[1,1,1]
	v_pk_fma_f32 v[86:87], v[86:87], v[62:63], v[94:95] op_sel:[0,1,0] op_sel_hi:[1,1,1]
	v_cvt_pk_bf16_f32 v12, v80, v81
	v_cvt_pk_bf16_f32 v13, v82, v83
	v_cvt_pk_bf16_f32 v14, v84, v85
	v_cvt_pk_bf16_f32 v15, v86, v87
	global_store_dwordx4 v[8:9], v[12:15], off
	v_lshl_add_u64 v[8:9], v[8:9], 0, s[10:11]
	s_waitcnt vmcnt(15)
	v_lshlrev_b32_e32 v88, 16, v16
	v_and_b32_e32 v89, 0xffff0000, v16
	v_lshlrev_b32_e32 v90, 16, v17
	v_and_b32_e32 v91, 0xffff0000, v17
	v_lshlrev_b32_e32 v92, 16, v18
	v_and_b32_e32 v93, 0xffff0000, v18
	v_lshlrev_b32_e32 v94, 16, v19
	v_and_b32_e32 v95, 0xffff0000, v19
	global_load_dwordx4 v[16:19], v[6:7], off
	v_lshl_add_u64 v[6:7], v[6:7], 0, s[10:11]
	v_pk_fma_f32 v[80:81], v[80:81], v[64:65], v[88:89] op_sel_hi:[1,0,1]
	v_pk_fma_f32 v[82:83], v[82:83], v[64:65], v[90:91] op_sel_hi:[1,0,1]
	v_pk_fma_f32 v[84:85], v[84:85], v[64:65], v[92:93] op_sel_hi:[1,0,1]
	v_pk_fma_f32 v[86:87], v[86:87], v[64:65], v[94:95] op_sel_hi:[1,0,1]
	v_cvt_pk_bf16_f32 v12, v80, v81
	v_cvt_pk_bf16_f32 v13, v82, v83
	v_cvt_pk_bf16_f32 v14, v84, v85
	v_cvt_pk_bf16_f32 v15, v86, v87
	global_store_dwordx4 v[8:9], v[12:15], off
	v_lshl_add_u64 v[8:9], v[8:9], 0, s[10:11]
	s_waitcnt vmcnt(15)
	v_lshlrev_b32_e32 v88, 16, v20
	v_and_b32_e32 v89, 0xffff0000, v20
	v_lshlrev_b32_e32 v90, 16, v21
	v_and_b32_e32 v91, 0xffff0000, v21
	v_lshlrev_b32_e32 v92, 16, v22
	v_and_b32_e32 v93, 0xffff0000, v22
	v_lshlrev_b32_e32 v94, 16, v23
	v_and_b32_e32 v95, 0xffff0000, v23
	global_load_dwordx4 v[20:23], v[6:7], off
	v_lshl_add_u64 v[6:7], v[6:7], 0, s[10:11]
	v_pk_fma_f32 v[80:81], v[80:81], v[64:65], v[88:89] op_sel:[0,1,0] op_sel_hi:[1,1,1]
	v_pk_fma_f32 v[82:83], v[82:83], v[64:65], v[90:91] op_sel:[0,1,0] op_sel_hi:[1,1,1]
	v_pk_fma_f32 v[84:85], v[84:85], v[64:65], v[92:93] op_sel:[0,1,0] op_sel_hi:[1,1,1]
	v_pk_fma_f32 v[86:87], v[86:87], v[64:65], v[94:95] op_sel:[0,1,0] op_sel_hi:[1,1,1]
	v_cvt_pk_bf16_f32 v12, v80, v81
	v_cvt_pk_bf16_f32 v13, v82, v83
	v_cvt_pk_bf16_f32 v14, v84, v85
	v_cvt_pk_bf16_f32 v15, v86, v87
	global_store_dwordx4 v[8:9], v[12:15], off
	v_lshl_add_u64 v[8:9], v[8:9], 0, s[10:11]
	s_waitcnt vmcnt(15)
	v_lshlrev_b32_e32 v88, 16, v24
	v_and_b32_e32 v89, 0xffff0000, v24
	v_lshlrev_b32_e32 v90, 16, v25
	v_and_b32_e32 v91, 0xffff0000, v25
	v_lshlrev_b32_e32 v92, 16, v26
	v_and_b32_e32 v93, 0xffff0000, v26
	v_lshlrev_b32_e32 v94, 16, v27
	v_and_b32_e32 v95, 0xffff0000, v27
	global_load_dwordx4 v[24:27], v[6:7], off
	v_lshl_add_u64 v[6:7], v[6:7], 0, s[10:11]
	v_pk_fma_f32 v[80:81], v[80:81], v[66:67], v[88:89] op_sel_hi:[1,0,1]
	v_pk_fma_f32 v[82:83], v[82:83], v[66:67], v[90:91] op_sel_hi:[1,0,1]
	v_pk_fma_f32 v[84:85], v[84:85], v[66:67], v[92:93] op_sel_hi:[1,0,1]
	v_pk_fma_f32 v[86:87], v[86:87], v[66:67], v[94:95] op_sel_hi:[1,0,1]
	v_cvt_pk_bf16_f32 v12, v80, v81
	v_cvt_pk_bf16_f32 v13, v82, v83
	v_cvt_pk_bf16_f32 v14, v84, v85
	v_cvt_pk_bf16_f32 v15, v86, v87
	global_store_dwordx4 v[8:9], v[12:15], off
	v_lshl_add_u64 v[8:9], v[8:9], 0, s[10:11]
	s_waitcnt vmcnt(15)
; __device__ __forceinline__ unsigned cvt_pk(float lo, float hi) { return pg8::cvt_pk_bf16(lo, hi); }
; __device__ __forceinline__ float bf_lo(unsigned u) { return __uint_as_float(u << 16); }
; __device__ __forceinline__ float bf_hi(unsigned u) { return __uint_as_float(u & 0xffff0000u); }
; __device__ __forceinline__ void s2_phase(const Bufs& B) {
;     ...
;         u32x4 nxt = *(const u32x4*)(B.states + base);
; #pragma unroll 4
;         for (int c = 0; c < NCHUNK; ++c) {
;             const size_t off = base + (size_t)c * 32 * 8192;
;             const u32x4 st = nxt;
;             if (c + 1 < NCHUNK) nxt = *(const u32x4*)(B.states + off + (size_t)32 * 8192);
;             u32x4 o;
; #pragma unroll
;             for (int q = 0; q < 4; ++q) o[q] = cvt_pk(hacc[2 * q], hacc[2 * q + 1]);
;             *(u32x4*)(B.hprev + off) = o;
;             const float dec = __expf(B.alast[(b * NCHUNK + c) * 32 + head]);
; #pragma unroll
;             for (int q = 0; q < 4; ++q) { hacc[2 * q] = hacc[2 * q] * dec + bf_lo(st[q]); hacc[2 * q + 1] = hacc[2 * q + 1] * dec + bf_hi(st[q]); }
;         }
	v_lshlrev_b32_e32 v88, 16, v28
	v_and_b32_e32 v89, 0xffff0000, v28
	v_lshlrev_b32_e32 v90, 16, v29
	v_and_b32_e32 v91, 0xffff0000, v29
	v_lshlrev_b32_e32 v92, 16, v30
	v_and_b32_e32 v93, 0xffff0000, v30
	v_lshlrev_b32_e32 v94, 16, v31
	v_and_b32_e32 v95, 0xffff0000, v31
	global_load_dwordx4 v[28:31], v[6:7], off
	v_lshl_add_u64 v[6:7], v[6:7], 0, s[10:11]
	v_pk_fma_f32 v[80:81], v[80:81], v[66:67], v[88:89] op_sel:[0,1,0] op_sel_hi:[1,1,1]
	v_pk_fma_f32 v[82:83], v[82:83], v[66:67], v[90:91] op_sel:[0,1,0] op_sel_hi:[1,1,1]
	v_pk_fma_f32 v[84:85], v[84:85], v[66:67], v[92:93] op_sel:[0,1,0] op_sel_hi:[1,1,1]
	v_pk_fma_f32 v[86:87], v[86:87], v[66:67], v[94:95] op_sel:[0,1,0] op_sel_hi:[1,1,1]
	v_cvt_pk_bf16_f32 v12, v80, v81
	v_cvt_pk_bf16_f32 v13, v82, v83
	v_cvt_pk_bf16_f32 v14, v84, v85
	v_cvt_pk_bf16_f32 v15, v86, v87
	global_store_dwordx4 v[8:9], v[12:15], off
	v_lshl_add_u64 v[8:9], v[8:9], 0, s[10:11]
	s_waitcnt vmcnt(15)
	v_lshlrev_b32_e32 v88, 16, v32
	v_and_b32_e32 v89, 0xffff0000, v32
	v_lshlrev_b32_e32 v90, 16, v33
	v_and_b32_e32 v91, 0xffff0000, v33
	v_lshlrev_b32_e32 v92, 16, v34
	v_and_b32_e32 v93, 0xffff0000, v34
	v_lshlrev_b32_e32 v94, 16, v35
	v_and_b32_e32 v95, 0xffff0000, v35
	global_load_dwordx4 v[32:35], v[6:7], off
	v_lshl_add_u64 v[6:7], v[6:7], 0, s[10:11]
	v_pk_fma_f32 v[80:81], v[80:81], v[68:69], v[88:89] op_sel_hi:[1,0,1]
	v_pk_fma_f32 v[82:83], v[82:83], v[68:69], v[90:91] op_sel_hi:[1,0,1]
	v_pk_fma_f32 v[84:85], v[84:85], v[68:69], v[92:93] op_sel_hi:[1,0,1]
	v_pk_fma_f32 v[86:87], v[86:87], v[68:69], v[94:95] op_sel_hi:[1,0,1]
	v_cvt_pk_bf16_f32 v12, v80, v81
	v_cvt_pk_bf16_f32 v13, v82, v83
	v_cvt_pk_bf16_f32 v14, v84, v85
	v_cvt_pk_bf16_f32 v15, v86, v87
	global_store_dwordx4 v[8:9], v[12:15], off
	v_lshl_add_u64 v[8:9], v[8:9], 0, s[10:11]
	s_waitcnt vmcnt(15)
	v_lshlrev_b32_e32 v88, 16, v36
	v_and_b32_e32 v89, 0xffff0000, v36
	v_lshlrev_b32_e32 v90, 16, v37
	v_and_b32_e32 v91, 0xffff0000, v37
	v_lshlrev_b32_e32 v92, 16, v38
	v_and_b32_e32 v93, 0xffff0000, v38
	v_lshlrev_b32_e32 v94, 16, v39
	v_and_b32_e32 v95, 0xffff0000, v39
	global_load_dwordx4 v[36:39], v[6:7], off
	v_lshl_add_u64 v[6:7], v[6:7], 0, s[10:11]
	v_pk_fma_f32 v[80:81], v[80:81], v[68:69], v[88:89] op_sel:[0,1,0] op_sel_hi:[1,1,1]
	v_pk_fma_f32 v[82:83], v[82:83], v[68:69], v[90:91] op_sel:[0,1,0] op_sel_hi:[1,1,1]
	v_pk_fma_f32 v[84:85], v[84:85], v[68:69], v[92:93] op_sel:[0,1,0] op_sel_hi:[1,1,1]
	v_pk_fma_f32 v[86:87], v[86:87], v[68:69], v[94:95] op_sel:[0,1,0] op_sel_hi:[1,1,1]
	v_cvt_pk_bf16_f32 v12, v80, v81
	v_cvt_pk_bf16_f32 v13, v82, v83
	v_cvt_pk_bf16_f32 v14, v84, v85
	v_cvt_pk_bf16_f32 v15, v86, v87
	global_store_dwordx4 v[8:9], v[12:15], off
	v_lshl_add_u64 v[8:9], v[8:9], 0, s[10:11]
	s_waitcnt vmcnt(15)
	v_lshlrev_b32_e32 v88, 16, v40
	v_and_b32_e32 v89, 0xffff0000, v40
	v_lshlrev_b32_e32 v90, 16, v41
	v_and_b32_e32 v91, 0xffff0000, v41
	v_lshlrev_b32_e32 v92, 16, v42
	v_and_b32_e32 v93, 0xffff0000, v42
	v_lshlrev_b32_e32 v94, 16, v43
	v_and_b32_e32 v95, 0xffff0000, v43
	global_load_dwordx4 v[40:43], v[6:7], off
	v_lshl_add_u64 v[6:7], v[6:7], 0, s[10:11]
	v_pk_fma_f32 v[80:81], v[80:81], v[70:71], v[88:89] op_sel_hi:[1,0,1]
	v_pk_fma_f32 v[82:83], v[82:83], v[70:71], v[90:91] op_sel_hi:[1,0,1]
	v_pk_fma_f32 v[84:85], v[84:85], v[70:71], v[92:93] op_sel_hi:[1,0,1]
	v_pk_fma_f32 v[86:87], v[86:87], v[70:71], v[94:95] op_sel_hi:[1,0,1]
	v_cvt_pk_bf16_f32 v12, v80, v81
	v_cvt_pk_bf16_f32 v13, v82, v83
	v_cvt_pk_bf16_f32 v14, v84, v85
	v_cvt_pk_bf16_f32 v15, v86, v87
	global_store_dwordx4 v[8:9], v[12:15], off
	v_lshl_add_u64 v[8:9], v[8:9], 0, s[10:11]
	s_waitcnt vmcnt(15)
	v_lshlrev_b32_e32 v88, 16, v44
	v_and_b32_e32 v89, 0xffff0000, v44
	v_lshlrev_b32_e32 v90, 16, v45
	v_and_b32_e32 v91, 0xffff0000, v45
	v_lshlrev_b32_e32 v92, 16, v46
	v_and_b32_e32 v93, 0xffff0000, v46
	v_lshlrev_b32_e32 v94, 16, v47
	v_and_b32_e32 v95, 0xffff0000, v47
	global_load_dwordx4 v[44:47], v[6:7], off
	v_pk_fma_f32 v[80:81], v[80:81], v[70:71], v[88:89] op_sel:[0,1,0] op_sel_hi:[1,1,1]
	v_pk_fma_f32 v[82:83], v[82:83], v[70:71], v[90:91] op_sel:[0,1,0] op_sel_hi:[1,1,1]
	v_pk_fma_f32 v[84:85], v[84:85], v[70:71], v[92:93] op_sel:[0,1,0] op_sel_hi:[1,1,1]
	v_pk_fma_f32 v[86:87], v[86:87], v[70:71], v[94:95] op_sel:[0,1,0] op_sel_hi:[1,1,1]
	v_cvt_pk_bf16_f32 v12, v80, v81
	v_cvt_pk_bf16_f32 v13, v82, v83
	v_cvt_pk_bf16_f32 v14, v84, v85
	v_cvt_pk_bf16_f32 v15, v86, v87
	global_store_dwordx4 v[8:9], v[12:15], off
	v_lshl_add_u64 v[8:9], v[8:9], 0, s[10:11]
	s_waitcnt vmcnt(15)
	v_lshlrev_b32_e32 v88, 16, v16
	v_and_b32_e32 v89, 0xffff0000, v16
	v_lshlrev_b32_e32 v90, 16, v17
	v_and_b32_e32 v91, 0xffff0000, v17
	v_lshlrev_b32_e32 v92, 16, v18
	v_and_b32_e32 v93, 0xffff0000, v18
	v_lshlrev_b32_e32 v94, 16, v19
	v_and_b32_e32 v95, 0xffff0000, v19
	v_pk_fma_f32 v[80:81], v[80:81], v[72:73], v[88:89] op_sel_hi:[1,0,1]
	v_pk_fma_f32 v[82:83], v[82:83], v[72:73], v[90:91] op_sel_hi:[1,0,1]
	v_pk_fma_f32 v[84:85], v[84:85], v[72:73], v[92:93] op_sel_hi:[1,0,1]
	v_pk_fma_f32 v[86:87], v[86:87], v[72:73], v[94:95] op_sel_hi:[1,0,1]
	v_cvt_pk_bf16_f32 v12, v80, v81
	v_cvt_pk_bf16_f32 v13, v82, v83
	v_cvt_pk_bf16_f32 v14, v84, v85
	v_cvt_pk_bf16_f32 v15, v86, v87
	global_store_dwordx4 v[8:9], v[12:15], off
	v_lshl_add_u64 v[8:9], v[8:9], 0, s[10:11]
	s_waitcnt vmcnt(14)
; __device__ __forceinline__ unsigned cvt_pk(float lo, float hi) { return pg8::cvt_pk_bf16(lo, hi); }
; __device__ __forceinline__ float bf_lo(unsigned u) { return __uint_as_float(u << 16); }
; __device__ __forceinline__ float bf_hi(unsigned u) { return __uint_as_float(u & 0xffff0000u); }
; __device__ __forceinline__ void s2_phase(const Bufs& B) {
;     ...
;         u32x4 nxt = *(const u32x4*)(B.states + base);
; #pragma unroll 4
;         for (int c = 0; c < NCHUNK; ++c) {
;             const size_t off = base + (size_t)c * 32 * 8192;
;             const u32x4 st = nxt;
;             if (c + 1 < NCHUNK) nxt = *(const u32x4*)(B.states + off + (size_t)32 * 8192);
;             u32x4 o;
; #pragma unroll
;             for (int q = 0; q < 4; ++q) o[q] = cvt_pk(hacc[2 * q], hacc[2 * q + 1]);
;             *(u32x4*)(B.hprev + off) = o;
;             const float dec = __expf(B.alast[(b * NCHUNK + c) * 32 + head]);
; #pragma unroll
;             for (int q = 0; q < 4; ++q) { hacc[2 * q] = hacc[2 * q] * dec + bf_lo(st[q]); hacc[2 * q + 1] = hacc[2 * q + 1] * dec + bf_hi(st[q]); }
;         }
	v_lshlrev_b32_e32 v88, 16, v20
	v_and_b32_e32 v89, 0xffff0000, v20
	v_lshlrev_b32_e32 v90, 16, v21
	v_and_b32_e32 v91, 0xffff0000, v21
	v_lshlrev_b32_e32 v92, 16, v22
	v_and_b32_e32 v93, 0xffff0000, v22
	v_lshlrev_b32_e32 v94, 16, v23
	v_and_b32_e32 v95, 0xffff0000, v23
	v_pk_fma_f32 v[80:81], v[80:81], v[72:73], v[88:89] op_sel:[0,1,0] op_sel_hi:[1,1,1]
	v_pk_fma_f32 v[82:83], v[82:83], v[72:73], v[90:91] op_sel:[0,1,0] op_sel_hi:[1,1,1]
	v_pk_fma_f32 v[84:85], v[84:85], v[72:73], v[92:93] op_sel:[0,1,0] op_sel_hi:[1,1,1]
	v_pk_fma_f32 v[86:87], v[86:87], v[72:73], v[94:95] op_sel:[0,1,0] op_sel_hi:[1,1,1]
	v_cvt_pk_bf16_f32 v12, v80, v81
	v_cvt_pk_bf16_f32 v13, v82, v83
	v_cvt_pk_bf16_f32 v14, v84, v85
	v_cvt_pk_bf16_f32 v15, v86, v87
	global_store_dwordx4 v[8:9], v[12:15], off
	v_lshl_add_u64 v[8:9], v[8:9], 0, s[10:11]
	s_waitcnt vmcnt(13)
	v_lshlrev_b32_e32 v88, 16, v24
	v_and_b32_e32 v89, 0xffff0000, v24
	v_lshlrev_b32_e32 v90, 16, v25
	v_and_b32_e32 v91, 0xffff0000, v25
	v_lshlrev_b32_e32 v92, 16, v26
	v_and_b32_e32 v93, 0xffff0000, v26
	v_lshlrev_b32_e32 v94, 16, v27
	v_and_b32_e32 v95, 0xffff0000, v27
	v_pk_fma_f32 v[80:81], v[80:81], v[74:75], v[88:89] op_sel_hi:[1,0,1]
	v_pk_fma_f32 v[82:83], v[82:83], v[74:75], v[90:91] op_sel_hi:[1,0,1]
	v_pk_fma_f32 v[84:85], v[84:85], v[74:75], v[92:93] op_sel_hi:[1,0,1]
	v_pk_fma_f32 v[86:87], v[86:87], v[74:75], v[94:95] op_sel_hi:[1,0,1]
	v_cvt_pk_bf16_f32 v12, v80, v81
	v_cvt_pk_bf16_f32 v13, v82, v83
	v_cvt_pk_bf16_f32 v14, v84, v85
	v_cvt_pk_bf16_f32 v15, v86, v87
	global_store_dwordx4 v[8:9], v[12:15], off
	v_lshl_add_u64 v[8:9], v[8:9], 0, s[10:11]
	s_waitcnt vmcnt(12)
	v_lshlrev_b32_e32 v88, 16, v28
	v_and_b32_e32 v89, 0xffff0000, v28
	v_lshlrev_b32_e32 v90, 16, v29
	v_and_b32_e32 v91, 0xffff0000, v29
	v_lshlrev_b32_e32 v92, 16, v30
	v_and_b32_e32 v93, 0xffff0000, v30
	v_lshlrev_b32_e32 v94, 16, v31
	v_and_b32_e32 v95, 0xffff0000, v31
	v_pk_fma_f32 v[80:81], v[80:81], v[74:75], v[88:89] op_sel:[0,1,0] op_sel_hi:[1,1,1]
	v_pk_fma_f32 v[82:83], v[82:83], v[74:75], v[90:91] op_sel:[0,1,0] op_sel_hi:[1,1,1]
	v_pk_fma_f32 v[84:85], v[84:85], v[74:75], v[92:93] op_sel:[0,1,0] op_sel_hi:[1,1,1]
	v_pk_fma_f32 v[86:87], v[86:87], v[74:75], v[94:95] op_sel:[0,1,0] op_sel_hi:[1,1,1]
	v_cvt_pk_bf16_f32 v12, v80, v81
	v_cvt_pk_bf16_f32 v13, v82, v83
	v_cvt_pk_bf16_f32 v14, v84, v85
	v_cvt_pk_bf16_f32 v15, v86, v87
	global_store_dwordx4 v[8:9], v[12:15], off
	v_lshl_add_u64 v[8:9], v[8:9], 0, s[10:11]
	s_waitcnt vmcnt(11)
	v_lshlrev_b32_e32 v88, 16, v32
	v_and_b32_e32 v89, 0xffff0000, v32
	v_lshlrev_b32_e32 v90, 16, v33
	v_and_b32_e32 v91, 0xffff0000, v33
	v_lshlrev_b32_e32 v92, 16, v34
	v_and_b32_e32 v93, 0xffff0000, v34
	v_lshlrev_b32_e32 v94, 16, v35
	v_and_b32_e32 v95, 0xffff0000, v35
	v_pk_fma_f32 v[80:81], v[80:81], v[76:77], v[88:89] op_sel_hi:[1,0,1]
	v_pk_fma_f32 v[82:83], v[82:83], v[76:77], v[90:91] op_sel_hi:[1,0,1]
	v_pk_fma_f32 v[84:85], v[84:85], v[76:77], v[92:93] op_sel_hi:[1,0,1]
	v_pk_fma_f32 v[86:87], v[86:87], v[76:77], v[94:95] op_sel_hi:[1,0,1]
	v_cvt_pk_bf16_f32 v12, v80, v81
	v_cvt_pk_bf16_f32 v13, v82, v83
	v_cvt_pk_bf16_f32 v14, v84, v85
	v_cvt_pk_bf16_f32 v15, v86, v87
	global_store_dwordx4 v[8:9], v[12:15], off
	v_lshl_add_u64 v[8:9], v[8:9], 0, s[10:11]
	s_waitcnt vmcnt(10)
	v_lshlrev_b32_e32 v88, 16, v36
	v_and_b32_e32 v89, 0xffff0000, v36
	v_lshlrev_b32_e32 v90, 16, v37
	v_and_b32_e32 v91, 0xffff0000, v37
	v_lshlrev_b32_e32 v92, 16, v38
	v_and_b32_e32 v93, 0xffff0000, v38
	v_lshlrev_b32_e32 v94, 16, v39
	v_and_b32_e32 v95, 0xffff0000, v39
	v_pk_fma_f32 v[80:81], v[80:81], v[76:77], v[88:89] op_sel:[0,1,0] op_sel_hi:[1,1,1]
	v_pk_fma_f32 v[82:83], v[82:83], v[76:77], v[90:91] op_sel:[0,1,0] op_sel_hi:[1,1,1]
	v_pk_fma_f32 v[84:85], v[84:85], v[76:77], v[92:93] op_sel:[0,1,0] op_sel_hi:[1,1,1]
	v_pk_fma_f32 v[86:87], v[86:87], v[76:77], v[94:95] op_sel:[0,1,0] op_sel_hi:[1,1,1]
	v_cvt_pk_bf16_f32 v12, v80, v81
	v_cvt_pk_bf16_f32 v13, v82, v83
	v_cvt_pk_bf16_f32 v14, v84, v85
	v_cvt_pk_bf16_f32 v15, v86, v87
	global_store_dwordx4 v[8:9], v[12:15], off
	v_lshl_add_u64 v[8:9], v[8:9], 0, s[10:11]
	s_waitcnt vmcnt(9)
	v_lshlrev_b32_e32 v88, 16, v40
	v_and_b32_e32 v89, 0xffff0000, v40
	v_lshlrev_b32_e32 v90, 16, v41
	v_and_b32_e32 v91, 0xffff0000, v41
	v_lshlrev_b32_e32 v92, 16, v42
	v_and_b32_e32 v93, 0xffff0000, v42
	v_lshlrev_b32_e32 v94, 16, v43
	v_and_b32_e32 v95, 0xffff0000, v43
	v_pk_fma_f32 v[80:81], v[80:81], v[78:79], v[88:89] op_sel_hi:[1,0,1]
	v_pk_fma_f32 v[82:83], v[82:83], v[78:79], v[90:91] op_sel_hi:[1,0,1]
	v_pk_fma_f32 v[84:85], v[84:85], v[78:79], v[92:93] op_sel_hi:[1,0,1]
	v_pk_fma_f32 v[86:87], v[86:87], v[78:79], v[94:95] op_sel_hi:[1,0,1]
	v_cvt_pk_bf16_f32 v12, v80, v81
	v_cvt_pk_bf16_f32 v13, v82, v83
	v_cvt_pk_bf16_f32 v14, v84, v85
	v_cvt_pk_bf16_f32 v15, v86, v87
	global_store_dwordx4 v[8:9], v[12:15], off
	s_branch .LBB0_207

; template <class Epi, class Sched, bool ALIGN_EPI = false, bool SP2 = false>
; __device__ __forceinline__ void gemm_phase(PG8_LAS unsigned char* lds, const Gemm g, const Sched& S, const Epi& E) {
;     ...
;         const bool has_next = S.next(ui + 1, nxt);
;         const char* nA = has_next ? (const char*)g.A + (size_t)nxt.pm * tstep : cA; const char* nB = has_next ? (const char*)g.Bt + (size_t)nxt.pn * tstep : cB;
;     ...
; #pragma unroll
;         for (int a = 0; a < 2; ++a)
; #pragma unroll
;             for (int b = 0; b < 2; ++b)
; #pragma unroll
;                 for (int m = 0; m < 4; ++m)
; #pragma unroll
;                     for (int n = 0; n < 2; ++n) acc[a][b][m][n] = (f32x4){0.f, 0.f, 0.f, 0.f};
;         cur = nxt; cA = nA; cB = nB; ++ui;
.LBB0_492:
	s_ashr_i32 s17, s16, 31
	s_lshl_b64 s[18:19], s[16:17], 19
	s_add_u32 s18, s94, s18
	s_addc_u32 s19, s95, s19
	s_and_b64 s[20:21], s[4:5], exec
	s_cselect_b32 s17, s19, s23
	s_cselect_b32 s46, s18, s22
	s_ashr_i32 s15, s14, 31
	s_lshl_b64 s[20:21], s[14:15], 19
	s_add_u32 s20, s28, s20
	s_addc_u32 s21, s29, s21
	s_and_b64 s[26:27], s[4:5], exec
	s_cselect_b32 s15, s21, s25
	s_cselect_b32 s47, s20, s24
	s_add_u32 s22, s22, 0x40080
	s_addc_u32 s23, s23, 0
	s_add_u32 s48, s24, 0x100
	v_mov_b32_e32 v2, 0
	s_addc_u32 s49, s25, 0
	s_mov_b32 s50, -2
	v_mov_b32_e32 v3, v2
	v_mov_b32_e32 v4, v2
	v_mov_b32_e32 v5, v2
	v_mov_b32_e32 v10, v2
	v_mov_b32_e32 v11, v2
	v_mov_b32_e32 v12, v2
	v_mov_b32_e32 v13, v2
	v_mov_b32_e32 v18, v2
	v_mov_b32_e32 v19, v2
	v_mov_b32_e32 v20, v2
	v_mov_b32_e32 v21, v2
	v_mov_b32_e32 v26, v2
	v_mov_b32_e32 v27, v2
	v_mov_b32_e32 v28, v2
	v_mov_b32_e32 v29, v2
	v_mov_b32_e32 v34, v2
	v_mov_b32_e32 v35, v2
	v_mov_b32_e32 v36, v2
	v_mov_b32_e32 v37, v2
	v_mov_b32_e32 v42, v2
	v_mov_b32_e32 v43, v2
	v_mov_b32_e32 v44, v2
	v_mov_b32_e32 v45, v2
	v_mov_b32_e32 v50, v2
	v_mov_b32_e32 v51, v2
	v_mov_b32_e32 v52, v2
	v_mov_b32_e32 v53, v2
	v_mov_b32_e32 v58, v2
	v_mov_b32_e32 v59, v2
	v_mov_b32_e32 v60, v2
	v_mov_b32_e32 v61, v2
	v_mov_b32_e32 v6, v2
	v_mov_b32_e32 v7, v2
	v_mov_b32_e32 v8, v2
	v_mov_b32_e32 v9, v2
	v_mov_b32_e32 v14, v2
	v_mov_b32_e32 v15, v2
	v_mov_b32_e32 v16, v2
	v_mov_b32_e32 v17, v2
	v_mov_b32_e32 v22, v2
	v_mov_b32_e32 v23, v2
	v_mov_b32_e32 v24, v2
	v_mov_b32_e32 v25, v2
	v_mov_b32_e32 v30, v2
	v_mov_b32_e32 v31, v2
	v_mov_b32_e32 v32, v2
	v_mov_b32_e32 v33, v2
	v_mov_b32_e32 v38, v2
	v_mov_b32_e32 v39, v2
	v_mov_b32_e32 v40, v2
	v_mov_b32_e32 v41, v2
	v_mov_b32_e32 v46, v2
	v_mov_b32_e32 v47, v2
	v_mov_b32_e32 v48, v2
	v_mov_b32_e32 v49, v2
	v_mov_b32_e32 v54, v2
	v_mov_b32_e32 v55, v2
	v_mov_b32_e32 v56, v2
	v_mov_b32_e32 v57, v2
	v_mov_b32_e32 v62, v2
	v_mov_b32_e32 v63, v2
	v_mov_b32_e32 v64, v2
	v_mov_b32_e32 v65, v2
	v_mov_b32_e32 v66, v2
	v_mov_b32_e32 v67, v2
	v_mov_b32_e32 v68, v2
	v_mov_b32_e32 v69, v2
	v_mov_b32_e32 v74, v2
	v_mov_b32_e32 v75, v2
	v_mov_b32_e32 v76, v2
	v_mov_b32_e32 v77, v2
	v_mov_b32_e32 v82, v2
	v_mov_b32_e32 v83, v2
	v_mov_b32_e32 v84, v2
	v_mov_b32_e32 v85, v2
	v_mov_b32_e32 v90, v2
	v_mov_b32_e32 v91, v2
	v_mov_b32_e32 v92, v2
	v_mov_b32_e32 v93, v2
	v_mov_b32_e32 v98, v2
	v_mov_b32_e32 v99, v2
	v_mov_b32_e32 v100, v2
	v_mov_b32_e32 v101, v2
	v_mov_b32_e32 v106, v2
	v_mov_b32_e32 v107, v2
	v_mov_b32_e32 v108, v2
	v_mov_b32_e32 v109, v2
	v_mov_b32_e32 v114, v2
	v_mov_b32_e32 v115, v2
	v_mov_b32_e32 v116, v2
	v_mov_b32_e32 v117, v2
	v_mov_b32_e32 v122, v2
	v_mov_b32_e32 v123, v2
	v_mov_b32_e32 v124, v2
	v_mov_b32_e32 v125, v2
	v_mov_b32_e32 v70, v2
	v_mov_b32_e32 v71, v2
	v_mov_b32_e32 v72, v2
	v_mov_b32_e32 v73, v2
	v_mov_b32_e32 v78, v2
	v_mov_b32_e32 v79, v2
	v_mov_b32_e32 v80, v2
	v_mov_b32_e32 v81, v2
	v_mov_b32_e32 v86, v2
	v_mov_b32_e32 v87, v2
	v_mov_b32_e32 v88, v2
	v_mov_b32_e32 v89, v2
	v_mov_b32_e32 v94, v2
	v_mov_b32_e32 v95, v2
	v_mov_b32_e32 v96, v2
	v_mov_b32_e32 v97, v2
	v_mov_b32_e32 v102, v2
	v_mov_b32_e32 v103, v2
	v_mov_b32_e32 v104, v2
	v_mov_b32_e32 v105, v2
	v_mov_b32_e32 v110, v2
	v_mov_b32_e32 v111, v2
	v_mov_b32_e32 v112, v2
	v_mov_b32_e32 v113, v2
	v_mov_b32_e32 v118, v2
	v_mov_b32_e32 v119, v2
	v_mov_b32_e32 v120, v2
	v_mov_b32_e32 v121, v2
	v_mov_b32_e32 v126, v2
	v_mov_b32_e32 v127, v2
	v_mov_b32_e32 v128, v2
	v_mov_b32_e32 v129, v2
